# split-phase XCC-leader release for B1->S5 and KV->X hand-offs (one L2 write-back per XCD instead of per workgroup)
# speedup vs baseline: 1.1009x; 1.0139x over previous
; DI int opaque_tid() { int t = threadIdx.x; asm volatile("" : "+v"(t)); return t; }
; DI void wait_count(unsigned* c, unsigned need) {
;     if (threadIdx.x == 0) {
;         while (__hip_atomic_load(c, __ATOMIC_RELAXED, __HIP_MEMORY_SCOPE_AGENT) < need) __builtin_amdgcn_s_sleep(1);
;         __builtin_amdgcn_fence(__ATOMIC_ACQUIRE, "agent");
;     }
;     __syncthreads();
; }
; DI void unit_S5(const Params& p, char* lds, int l, int b, int g) {
;     const int tid = opaque_tid(), lane = tid & 63, wid = tid >> 6, l15 = lane & 15, quad = lane >> 4;
;     const int lg = l * 16 + g;
;     const bf16_t* T = WS_PTR(const bf16_t, OFF_S5T) + (size_t)lg * 3 * 16384;
;     float* HLb = (float*)lds;
;     float* EndS = (float*)(lds + 67584);
;     bf16x8 wst[4], wintra[4], wcar[4];
; #pragma unroll
;     for (int ks = 0; ks < 4; ++ks) {
;         wintra[ks] = *(const bf16x8*)(T + (16 * wid + l15) * 128 + 32 * ks + 8 * quad);
;         wst[ks] = *(const bf16x8*)(T + 16384 + (16 * wid + l15) * 128 + 32 * ks + 8 * quad);
;         wcar[ks] = *(const bf16x8*)(T + 32768 + (16 * wid + l15) * 128 + 32 * ks + 8 * quad);
;     }
;     const f32x2 L8 = WS_PTR(const f32x2, OFF_L8)[lg * 64 + lane], L128 = WS_PTR(const f32x2, OFF_L128)[lg * 64 + lane];
;     const bf16_t* Xg = WS_PTR(const bf16_t, OFF_XBB) + ((size_t)(b * 16 + g) * 2048) * 16;
;     bf16_t* YSo = WS_PTR(bf16_t, OFF_YS) + (size_t)b * 2048 * 256 + 16 * g;
;     const float dsk = p.ssm_d[l * 256 + 16 * g + l15];
;     char* Xl = lds + 75776;
;     __syncthreads();
;     wait_count(WS_PTR(unsigned, OFF_HL) + 128 + l * 16 + b, 16u);
.LBB0_663:
	s_cmpk_gt_i32 s2, 0xff
	s_mov_b64 s[6:7], -1
	s_cbranch_scc0 .LBB0_892
	s_add_i32 s3, s2, 0xffffff00
	s_cmp_ge_i32 s3, s24
	s_cbranch_scc0 .LBB0_859
	s_sub_i32 s79, s3, s24
	s_cmpk_gt_i32 s79, 0x3ff
	s_cbranch_scc0 .LBB0_825
	s_and_b32 s40, s2, 7
	s_bfe_u32 s73, s2, 0x50003
	s_cmpk_gt_u32 s79, 0x4ff
	s_cbranch_scc0 .LBB0_740
	s_lshl_b32 s0, s40, 1
	s_lshr_b32 s1, s73, 4
	s_or_b32 s0, s1, s0
	s_bfe_u32 s1, s2, 0x40003
	v_mov_b32_e32 v50, v212
	v_readlane_b32 s6, v243, 63
	v_readlane_b32 s7, v242, 0
	v_and_b32_e32 v54, 15, v50
	s_or_b32 s8, s1, s6
	v_ashrrev_i32_e32 v104, 6, v50
	s_mul_i32 s6, s8, 0x18000
	v_readlane_b32 s7, v244, 58
	v_lshlrev_b32_e32 v0, 7, v54
	s_add_u32 s6, s7, s6
	v_readlane_b32 s7, v244, 59
	v_lshl_or_b32 v2, v104, 11, v0
	s_addc_u32 s7, s7, 0
	v_ashrrev_i32_e32 v3, 31, v2
	v_lshl_add_u64 v[2:3], v[2:3], 1, s[6:7]
	v_and_b32_e32 v0, 48, v50
	v_lshl_add_u64 v[18:19], v[2:3], 0, v[0:1]
	s_mov_b64 s[6:7], 0x8000
	v_lshl_add_u64 v[26:27], v[18:19], 0, s[6:7]
	s_mov_b64 s[6:7], 0x10000
	v_lshl_add_u64 v[30:31], v[18:19], 0, s[6:7]
	s_mov_b32 s6, 0x8000
	v_add_co_u32_e32 v2, vcc, s6, v18
	s_mov_b32 s6, 0x10000
	s_nop 0
	v_addc_co_u32_e32 v3, vcc, 0, v19, vcc
	v_add_co_u32_e32 v4, vcc, s6, v18
	v_and_b32_e32 v56, 63, v50
	s_nop 0
	v_addc_co_u32_e32 v5, vcc, 0, v19, vcc
	global_load_dwordx4 v[34:37], v[2:3], off
	s_nop 0
	global_load_dwordx4 v[2:5], v[4:5], off
	s_nop 0
	global_load_dwordx4 v[6:9], v[18:19], off
	global_load_dwordx4 v[10:13], v[18:19], off offset:64
	global_load_dwordx4 v[38:41], v[26:27], off offset:64
	global_load_dwordx4 v[42:45], v[26:27], off offset:128
	global_load_dwordx4 v[14:17], v[18:19], off offset:128
	s_nop 0
	global_load_dwordx4 v[18:21], v[18:19], off offset:192
	s_nop 0
	global_load_dwordx4 v[22:25], v[30:31], off offset:64
	global_load_dwordx4 v[46:49], v[26:27], off offset:192
	s_nop 0
	global_load_dwordx4 v[26:29], v[30:31], off offset:128
	s_nop 0
	global_load_dwordx4 v[30:33], v[30:31], off offset:192
	v_lshl_or_b32 v52, s8, 6, v56
	v_mov_b32_e32 v53, v1
	v_readlane_b32 s6, v244, 60
	v_lshlrev_b64 v[52:53], 3, v[52:53]
	v_readlane_b32 s7, v244, 61
	s_lshl_b32 s78, s1, 4
	v_readlane_b32 s8, v244, 20
	v_lshl_add_u64 v[58:59], s[6:7], 0, v[52:53]
	v_readlane_b32 s6, v244, 62
	v_readlane_b32 s7, v244, 63
	v_readlane_b32 s20, v244, 32
	v_readlane_b32 s21, v244, 33
	v_lshl_add_u64 v[52:53], s[6:7], 0, v[52:53]
	v_readlane_b32 s6, v243, 62
	s_or_b32 s6, s78, s6
	global_load_dwordx2 v[58:59], v[58:59], off
	s_nop 0
	global_load_dwordx2 v[60:61], v[52:53], off
	v_or_b32_e32 v52, s6, v54
	v_mov_b32_e32 v53, v1
	v_lshl_add_u64 v[52:53], v[52:53], 2, s[20:21]
	global_load_dword v55, v[52:53], off
	v_readlane_b32 s9, v244, 21
	v_readlane_b32 s10, v244, 22
	v_readlane_b32 s11, v244, 23
	v_readlane_b32 s12, v244, 24
	v_readlane_b32 s13, v244, 25
	v_readlane_b32 s14, v244, 26
	v_readlane_b32 s15, v244, 27
	v_readlane_b32 s16, v244, 28
	v_readlane_b32 s17, v244, 29
	v_readlane_b32 s18, v244, 30
	v_readlane_b32 s19, v244, 31
	v_readlane_b32 s22, v244, 34
	v_readlane_b32 s23, v244, 35
	s_barrier
	s_mov_b64 s[6:7], exec
	v_readlane_b32 s8, v243, 32
	v_readlane_b32 s9, v243, 33
	s_and_b64 s[8:9], s[6:7], s[8:9]
	s_mov_b64 exec, s[8:9]
	s_cbranch_execz .LBB0_671
	v_readlane_b32 s10, v244, 42
	v_readlane_b32 s11, v244, 43
	v_readlane_b32 s8, v243, 38
	v_readlane_b32 s9, v245, 1
	s_nop 3
	s_lshr_b32 s8, s8, 1
	s_add_u32 s8, s8, 1
	s_mul_i32 s8, s8, s9
.Lxs_s5_wait:
	global_load_dword v51, v1, s[10:11] offset:840 sc1
	s_waitcnt vmcnt(0)
	v_cmp_gt_u32_e32 vcc, s8, v51
	s_cbranch_vccz .Lxs_s5_ok
	s_sleep 1
	s_branch .Lxs_s5_wait

; DI void wait_count(unsigned* c, unsigned need) {
;     if (threadIdx.x == 0) {
;         while (__hip_atomic_load(c, __ATOMIC_RELAXED, __HIP_MEMORY_SCOPE_AGENT) < need) __builtin_amdgcn_s_sleep(1);
;         __builtin_amdgcn_fence(__ATOMIC_ACQUIRE, "agent");
;     }
;     __syncthreads();
; }
; DI void unit_X(const Params& p, char* lds, int l, int chunk) {
;     ...
;     if (l == 0) wait_count(WS_PTR(unsigned, OFF_HL) + 64 + l * 16 + b, 8u); else __syncthreads();
.LBB0_817:
	s_andn2_b64 vcc, exec, s[6:7]
	s_lshr_b32 s0, s8, 4
	s_cbranch_vccnz .LBB0_823
	s_mov_b64 s[6:7], exec
	v_readlane_b32 s8, v243, 32
	v_readlane_b32 s9, v243, 33
	s_and_b64 s[8:9], s[6:7], s[8:9]
	s_mov_b64 exec, s[8:9]
	s_cbranch_execz .LBB0_822
	v_readlane_b32 s8, v244, 42
	v_readlane_b32 s9, v244, 43
	v_readlane_b32 s1, v245, 1
	s_nop 4
.Lxs_x_wait:
	global_load_dword v0, v1, s[8:9] offset:844 sc1
	s_waitcnt vmcnt(0)
	v_cmp_gt_u32_e32 vcc, s1, v0
	s_cbranch_vccz .Lxs_x_ok
	s_sleep 1
	s_branch .Lxs_x_wait

; template <int N> DI void wait_vm() { asm volatile("s_waitcnt vmcnt(%0)" ::"n"(N) : "memory"); }
; DI void signal_done(unsigned* c) {
;     wait_vm<0>();
;     __syncthreads();
;     if (threadIdx.x == 0) { __builtin_amdgcn_fence(__ATOMIC_RELEASE, "agent"); __hip_atomic_fetch_add(c, 1u, __ATOMIC_RELAXED, __HIP_MEMORY_SCOPE_AGENT); }
; }
; DI void unit_KV(const Params& p, char* lds, int l, int mtile, int q) {
;     ...
;     signal_done(WS_PTR(unsigned, OFF_HL) + 64 + l * 16 + (mtile >> 1));
.LBB0_887:
	s_waitcnt vmcnt(0)
	s_barrier
	s_mov_b64 s[6:7], exec
	v_readlane_b32 s8, v243, 32
	v_readlane_b32 s9, v243, 33
	s_and_b64 s[8:9], s[6:7], s[8:9]
	s_mov_b64 exec, s[8:9]
	s_cbranch_execz .LBB0_890
	v_readlane_b32 s10, v244, 42
	v_readlane_b32 s11, v244, 43
	s_getreg_b32 s0, hwreg(HW_REG_XCC_ID, 0, 4)
	s_lshl_b32 s0, s0, 2
	v_mov_b32_e32 v2, s0
	v_mov_b32_e32 v3, 1
	v_readlane_b32 s8, v245, 0
	s_nop 3
	s_cmp_lg_u32 s8, 0
	s_cbranch_scc1 .Lcen_kv_done
	v_readlane_b32 s0, v244, 18
.Lcen_kv_loop:
	global_load_dwordx4 v[4:7], v1, s[10:11] offset:640 sc1
	global_load_dwordx4 v[8:11], v1, s[10:11] offset:656 sc1
	global_load_dwordx4 v[12:15], v1, s[10:11] offset:672 sc1
	global_load_dwordx4 v[16:19], v1, s[10:11] offset:688 sc1
	global_load_dword v20, v2, s[10:11] offset:640 sc1
	s_waitcnt vmcnt(0)
	v_add3_u32 v21, v4, v5, v6
	v_add3_u32 v21, v21, v7, v8
	v_add3_u32 v21, v21, v9, v10
	v_add3_u32 v21, v21, v11, v12
	v_add3_u32 v21, v21, v13, v14
	v_add3_u32 v21, v21, v15, v16
	v_add3_u32 v21, v21, v17, v18
	v_add_u32_e32 v21, v21, v19
	v_cmp_ne_u32_e32 vcc, s0, v21
	s_cbranch_vccz .Lcen_kv_ok
	s_sleep 2
	s_branch .Lcen_kv_loop
.Lcen_kv_ok:
	v_mov_b32_e32 v22, 0
	v_cmp_ne_u32_e32 vcc, 0, v4
	s_nop 1
	v_addc_co_u32_e32 v22, vcc, 0, v22, vcc
	v_cmp_ne_u32_e32 vcc, 0, v5
	s_nop 1
	v_addc_co_u32_e32 v22, vcc, 0, v22, vcc
	v_cmp_ne_u32_e32 vcc, 0, v6
	s_nop 1
	v_addc_co_u32_e32 v22, vcc, 0, v22, vcc
	v_cmp_ne_u32_e32 vcc, 0, v7
	s_nop 1
	v_addc_co_u32_e32 v22, vcc, 0, v22, vcc
	v_cmp_ne_u32_e32 vcc, 0, v8
	s_nop 1
	v_addc_co_u32_e32 v22, vcc, 0, v22, vcc
	v_cmp_ne_u32_e32 vcc, 0, v9
	s_nop 1
	v_addc_co_u32_e32 v22, vcc, 0, v22, vcc
	v_cmp_ne_u32_e32 vcc, 0, v10
	s_nop 1
	v_addc_co_u32_e32 v22, vcc, 0, v22, vcc
	v_cmp_ne_u32_e32 vcc, 0, v11
	s_nop 1
	v_addc_co_u32_e32 v22, vcc, 0, v22, vcc
	v_cmp_ne_u32_e32 vcc, 0, v12
	s_nop 1
	v_addc_co_u32_e32 v22, vcc, 0, v22, vcc
	v_cmp_ne_u32_e32 vcc, 0, v13
	s_nop 1
	v_addc_co_u32_e32 v22, vcc, 0, v22, vcc
	v_cmp_ne_u32_e32 vcc, 0, v14
	s_nop 1
	v_addc_co_u32_e32 v22, vcc, 0, v22, vcc
	v_cmp_ne_u32_e32 vcc, 0, v15
	s_nop 1
	v_addc_co_u32_e32 v22, vcc, 0, v22, vcc
	v_cmp_ne_u32_e32 vcc, 0, v16
	s_nop 1
	v_addc_co_u32_e32 v22, vcc, 0, v22, vcc
	v_cmp_ne_u32_e32 vcc, 0, v17
	s_nop 1
	v_addc_co_u32_e32 v22, vcc, 0, v22, vcc
	v_cmp_ne_u32_e32 vcc, 0, v18
	s_nop 1
	v_addc_co_u32_e32 v22, vcc, 0, v22, vcc
	v_cmp_ne_u32_e32 vcc, 0, v19
	s_nop 1
	v_addc_co_u32_e32 v22, vcc, 0, v22, vcc
	v_readfirstlane_b32 s8, v20
	v_readfirstlane_b32 s9, v22
	s_nop 3
	v_writelane_b32 v245, s8, 0
	v_writelane_b32 v245, s9, 1
.Lcen_kv_done:
	global_atomic_add v0, v2, v3, s[10:11] offset:448 sc0
	s_waitcnt vmcnt(0)
	v_readfirstlane_b32 s9, v0
	s_nop 3
	s_add_u32 s9, s9, 1
	s_cmp_eq_u32 s9, s8
	s_cbranch_scc0 .LBB0_890
	buffer_wbl2 sc1
	s_waitcnt vmcnt(0)
	global_atomic_add v1, v3, s[10:11] offset:844

; template <int N> DI void wait_vm() { asm volatile("s_waitcnt vmcnt(%0)" ::"n"(N) : "memory"); }
; DI void signal_done(unsigned* c) {
;     wait_vm<0>();
;     __syncthreads();
;     if (threadIdx.x == 0) { __builtin_amdgcn_fence(__ATOMIC_RELEASE, "agent"); __hip_atomic_fetch_add(c, 1u, __ATOMIC_RELAXED, __HIP_MEMORY_SCOPE_AGENT); }
; }
; DI void unit_B1(const Params& p, char* lds, int l, int chunk) {
;     ...
;     signal_done(WS_PTR(unsigned, OFF_HL) + 128 + l * 16 + (chunk >> 4));
.LBB0_981:
	s_or_b64 exec, exec, s[8:9]
	s_waitcnt vmcnt(0)
	s_waitcnt vmcnt(63) expcnt(7) lgkmcnt(15)
	s_barrier
	s_mov_b64 s[8:9], exec
	v_readlane_b32 s0, v243, 32
	v_readlane_b32 s1, v243, 33
	s_and_b64 s[0:1], s[8:9], s[0:1]
	s_mov_b64 exec, s[0:1]
	s_cbranch_execz .LBB0_661
	v_readlane_b32 s10, v244, 42
	v_readlane_b32 s11, v244, 43
	s_getreg_b32 s0, hwreg(HW_REG_XCC_ID, 0, 4)
	s_lshl_b32 s0, s0, 2
	v_mov_b32_e32 v2, s0
	v_mov_b32_e32 v3, 1
	v_readlane_b32 s3, v245, 0
	s_nop 3
	s_cmp_lg_u32 s3, 0
	s_cbranch_scc1 .Lcen_b1_done
	v_readlane_b32 s0, v244, 18

; template <int N> DI void wait_vm() { asm volatile("s_waitcnt vmcnt(%0)" ::"n"(N) : "memory"); }
; DI void signal_done(unsigned* c) {
;     wait_vm<0>();
;     __syncthreads();
;     if (threadIdx.x == 0) { __builtin_amdgcn_fence(__ATOMIC_RELEASE, "agent"); __hip_atomic_fetch_add(c, 1u, __ATOMIC_RELAXED, __HIP_MEMORY_SCOPE_AGENT); }
; }
; DI void unit_B1(const Params& p, char* lds, int l, int chunk) {
;     ...
;     signal_done(WS_PTR(unsigned, OFF_HL) + 128 + l * 16 + (chunk >> 4));
.Lcen_b1_ok:
	v_mov_b32_e32 v22, 0
	v_cmp_ne_u32_e32 vcc, 0, v4
	s_nop 1
	v_addc_co_u32_e32 v22, vcc, 0, v22, vcc
	v_cmp_ne_u32_e32 vcc, 0, v5
	s_nop 1
	v_addc_co_u32_e32 v22, vcc, 0, v22, vcc
	v_cmp_ne_u32_e32 vcc, 0, v6
	s_nop 1
	v_addc_co_u32_e32 v22, vcc, 0, v22, vcc
	v_cmp_ne_u32_e32 vcc, 0, v7
	s_nop 1
	v_addc_co_u32_e32 v22, vcc, 0, v22, vcc
	v_cmp_ne_u32_e32 vcc, 0, v8
	s_nop 1
	v_addc_co_u32_e32 v22, vcc, 0, v22, vcc
	v_cmp_ne_u32_e32 vcc, 0, v9
	s_nop 1
	v_addc_co_u32_e32 v22, vcc, 0, v22, vcc
	v_cmp_ne_u32_e32 vcc, 0, v10
	s_nop 1
	v_addc_co_u32_e32 v22, vcc, 0, v22, vcc
	v_cmp_ne_u32_e32 vcc, 0, v11
	s_nop 1
	v_addc_co_u32_e32 v22, vcc, 0, v22, vcc
	v_cmp_ne_u32_e32 vcc, 0, v12
	s_nop 1
	v_addc_co_u32_e32 v22, vcc, 0, v22, vcc
	v_cmp_ne_u32_e32 vcc, 0, v13
	s_nop 1
	v_addc_co_u32_e32 v22, vcc, 0, v22, vcc
	v_cmp_ne_u32_e32 vcc, 0, v14
	s_nop 1
	v_addc_co_u32_e32 v22, vcc, 0, v22, vcc
	v_cmp_ne_u32_e32 vcc, 0, v15
	s_nop 1
	v_addc_co_u32_e32 v22, vcc, 0, v22, vcc
	v_cmp_ne_u32_e32 vcc, 0, v16
	s_nop 1
	v_addc_co_u32_e32 v22, vcc, 0, v22, vcc
	v_cmp_ne_u32_e32 vcc, 0, v17
	s_nop 1
	v_addc_co_u32_e32 v22, vcc, 0, v22, vcc
	v_cmp_ne_u32_e32 vcc, 0, v18
	s_nop 1
	v_addc_co_u32_e32 v22, vcc, 0, v22, vcc
	v_cmp_ne_u32_e32 vcc, 0, v19
	s_nop 1
	v_addc_co_u32_e32 v22, vcc, 0, v22, vcc
	v_readfirstlane_b32 s3, v20
	v_readfirstlane_b32 s6, v22
	s_nop 3
	v_writelane_b32 v245, s3, 0
	v_writelane_b32 v245, s6, 1
.Lcen_b1_done:
	v_readlane_b32 s1, v243, 38
	s_nop 3
	s_lshr_b32 s1, s1, 1
	s_add_u32 s1, s1, 1
	global_atomic_add v0, v2, v3, s[10:11] offset:384 sc0
	s_waitcnt vmcnt(0)
	v_readfirstlane_b32 s6, v0
	s_nop 3
	s_add_u32 s6, s6, 1
	s_mul_i32 s7, s1, s3
	s_cmp_eq_u32 s6, s7
	s_cbranch_scc0 .LBB0_661
	buffer_wbl2 sc1
	s_waitcnt vmcnt(0)
	global_atomic_add v1, v3, s[10:11] offset:840
	s_branch .LBB0_661
